# P0: batched silu(cond) fill and sg_w conversion loads; free WGs take 8 transposes items each
# baseline (speedup 1.0000x reference)
; __device__ __forceinline__ unsigned cvtpk(float lo, float hi) { f32x2 v = {lo, hi}; bf16x2_t b = __builtin_convertvector(v, bf16x2_t); return __builtin_bit_cast(unsigned, b); }
; __device__ __forceinline__ void p0_prologue(const Args& a, LAS unsigned char* lds, int tid, int wid, int lane, int G) {
;     ...
;     } else if ((int)blockIdx.x == G - 2) {
;         bf16_t* sw = (bf16_t*)(ws + WS_SGW);
;         for (int i = tid; i < 8 * 128 * 128 / 2; i += 512) ((unsigned*)sw)[i] = cvtpk(a.sg_w[2 * i], a.sg_w[2 * i + 1]);
.LBB0_17:
	v_and_b32_e32 v177, 63, v176
	s_cmpk_gt_i32 s2, 0xbf
	s_mov_b64 s[4:5], -1
	s_cbranch_scc0 .LBB0_37
	s_add_i32 s3, s30, -1
	s_cmp_lg_u32 s2, s3
	s_cbranch_scc0 .LBB0_24
	s_add_i32 s3, s30, -2
	s_cmp_lg_u32 s2, s3
	s_cbranch_scc1 .LBB0_23
	v_lshlrev_b32_e32 v2, 2, v176
	v_mov_b32_e32 v3, 0
	v_lshl_add_u64 v[0:1], s[28:29], 0, v[2:3]
	s_mov_b64 s[4:5], 0x90000
	v_lshlrev_b32_e32 v2, 3, v176
	v_add_u32_e32 v4, 0xfffffe00, v176
	v_lshl_add_u64 v[0:1], v[0:1], 0, s[4:5]
	v_lshl_add_u64 v[2:3], s[44:45], 0, v[2:3]
	s_mov_b64 s[4:5], 0
	s_mov_b64 s[8:9], 0x800
	s_mov_b64 s[10:11], 0x1000
	s_mov_b32 s3, 0xfdff
	s_movk_i32 s3, 8
.Lsgw_loop:
	global_load_dwordx2 v[128:129], v[2:3], off
	v_lshl_add_u64 v[2:3], v[2:3], 0, s[10:11]
	global_load_dwordx2 v[130:131], v[2:3], off
	v_lshl_add_u64 v[2:3], v[2:3], 0, s[10:11]
	global_load_dwordx2 v[132:133], v[2:3], off
	v_lshl_add_u64 v[2:3], v[2:3], 0, s[10:11]
	global_load_dwordx2 v[134:135], v[2:3], off
	v_lshl_add_u64 v[2:3], v[2:3], 0, s[10:11]
	global_load_dwordx2 v[136:137], v[2:3], off
	v_lshl_add_u64 v[2:3], v[2:3], 0, s[10:11]
	global_load_dwordx2 v[138:139], v[2:3], off
	v_lshl_add_u64 v[2:3], v[2:3], 0, s[10:11]
	global_load_dwordx2 v[140:141], v[2:3], off
	v_lshl_add_u64 v[2:3], v[2:3], 0, s[10:11]
	global_load_dwordx2 v[142:143], v[2:3], off
	v_lshl_add_u64 v[2:3], v[2:3], 0, s[10:11]
	global_load_dwordx2 v[144:145], v[2:3], off
	v_lshl_add_u64 v[2:3], v[2:3], 0, s[10:11]
	global_load_dwordx2 v[146:147], v[2:3], off
	v_lshl_add_u64 v[2:3], v[2:3], 0, s[10:11]
	global_load_dwordx2 v[148:149], v[2:3], off
	v_lshl_add_u64 v[2:3], v[2:3], 0, s[10:11]
	global_load_dwordx2 v[150:151], v[2:3], off
	v_lshl_add_u64 v[2:3], v[2:3], 0, s[10:11]
	global_load_dwordx2 v[152:153], v[2:3], off
	v_lshl_add_u64 v[2:3], v[2:3], 0, s[10:11]
	global_load_dwordx2 v[154:155], v[2:3], off
	v_lshl_add_u64 v[2:3], v[2:3], 0, s[10:11]
	global_load_dwordx2 v[156:157], v[2:3], off
	v_lshl_add_u64 v[2:3], v[2:3], 0, s[10:11]
	global_load_dwordx2 v[158:159], v[2:3], off
	v_lshl_add_u64 v[2:3], v[2:3], 0, s[10:11]
	s_waitcnt vmcnt(0)
	v_cvt_pk_bf16_f32 v160, v128, v129
	v_cvt_pk_bf16_f32 v161, v130, v131
	v_cvt_pk_bf16_f32 v162, v132, v133
	v_cvt_pk_bf16_f32 v163, v134, v135
	v_cvt_pk_bf16_f32 v164, v136, v137
	v_cvt_pk_bf16_f32 v166, v138, v139
	v_cvt_pk_bf16_f32 v167, v140, v141
	v_cvt_pk_bf16_f32 v168, v142, v143
	v_cvt_pk_bf16_f32 v169, v144, v145
	v_cvt_pk_bf16_f32 v170, v146, v147
	v_cvt_pk_bf16_f32 v171, v148, v149
	v_cvt_pk_bf16_f32 v172, v150, v151
	v_cvt_pk_bf16_f32 v173, v152, v153
	v_cvt_pk_bf16_f32 v174, v154, v155
	v_cvt_pk_bf16_f32 v175, v156, v157
	v_cvt_pk_bf16_f32 v178, v158, v159
	global_store_dword v[0:1], v160, off
	v_lshl_add_u64 v[0:1], v[0:1], 0, s[8:9]
	global_store_dword v[0:1], v161, off
	v_lshl_add_u64 v[0:1], v[0:1], 0, s[8:9]
	global_store_dword v[0:1], v162, off
	v_lshl_add_u64 v[0:1], v[0:1], 0, s[8:9]
	global_store_dword v[0:1], v163, off
	v_lshl_add_u64 v[0:1], v[0:1], 0, s[8:9]
	global_store_dword v[0:1], v164, off
	v_lshl_add_u64 v[0:1], v[0:1], 0, s[8:9]
	global_store_dword v[0:1], v166, off
	v_lshl_add_u64 v[0:1], v[0:1], 0, s[8:9]
	global_store_dword v[0:1], v167, off
	v_lshl_add_u64 v[0:1], v[0:1], 0, s[8:9]
	global_store_dword v[0:1], v168, off
	v_lshl_add_u64 v[0:1], v[0:1], 0, s[8:9]
	global_store_dword v[0:1], v169, off
	v_lshl_add_u64 v[0:1], v[0:1], 0, s[8:9]
	global_store_dword v[0:1], v170, off
	v_lshl_add_u64 v[0:1], v[0:1], 0, s[8:9]
	global_store_dword v[0:1], v171, off
	v_lshl_add_u64 v[0:1], v[0:1], 0, s[8:9]
	global_store_dword v[0:1], v172, off
	v_lshl_add_u64 v[0:1], v[0:1], 0, s[8:9]
	global_store_dword v[0:1], v173, off
	v_lshl_add_u64 v[0:1], v[0:1], 0, s[8:9]
	global_store_dword v[0:1], v174, off
	v_lshl_add_u64 v[0:1], v[0:1], 0, s[8:9]
	global_store_dword v[0:1], v175, off
	v_lshl_add_u64 v[0:1], v[0:1], 0, s[8:9]
	global_store_dword v[0:1], v178, off
	v_lshl_add_u64 v[0:1], v[0:1], 0, s[8:9]
	s_add_i32 s3, s3, -1
	s_cmp_lg_u32 s3, 0
	s_cbranch_scc1 .Lsgw_loop
	s_or_b64 exec, exec, s[4:5]

; __device__ __forceinline__ float fast_silu(float x) { return x * fast_sigmoid(x); }
; __device__ __forceinline__ void p0_prologue(const Args& a, LAS unsigned char* lds, int tid, int wid, int lane, int G) {
;     ...
;         for (int i = tid; i < 9 * DM; i += 512) { const float v = i < 8 * DM ? a.c[i] : a.c_ctx[i - 8 * DM]; sl[i] = fast_silu(v); }
.LBB0_37:
	s_load_dwordx16 s[8:23], s[0:1], 0x0
	s_andn2_b64 vcc, exec, s[4:5]
	s_lshr_b32 s92, s97, 6
	s_waitcnt lgkmcnt(0)
	v_writelane_b32 v242, s8, 11
	s_nop 1
	v_writelane_b32 v242, s9, 12
	v_writelane_b32 v242, s10, 13
	v_writelane_b32 v242, s11, 14
	v_writelane_b32 v242, s12, 15
	v_writelane_b32 v242, s13, 16
	v_writelane_b32 v242, s14, 17
	v_writelane_b32 v242, s15, 18
	v_writelane_b32 v242, s16, 19
	v_writelane_b32 v242, s17, 20
	v_writelane_b32 v242, s18, 21
	v_writelane_b32 v242, s19, 22
	v_writelane_b32 v242, s20, 23
	v_writelane_b32 v242, s21, 24
	v_writelane_b32 v242, s22, 25
	v_writelane_b32 v242, s23, 26
	s_cbranch_vccnz .LBB0_46
	v_readlane_b32 s4, v242, 11
	v_lshlrev_b32_e32 v0, 2, v176
	v_mov_b32_e32 v1, 0
	v_readlane_b32 s10, v242, 17
	v_readlane_b32 s11, v242, 18
	s_mov_b32 s0, 0xffff0000
	v_readlane_b32 s5, v242, 12
	v_readlane_b32 s6, v242, 13
	v_readlane_b32 s7, v242, 14
	v_lshl_add_u64 v[2:3], s[10:11], 0, v[0:1]
	s_mov_b32 s1, -1
	v_add_u32_e32 v6, 0, v0
	v_lshl_add_u64 v[2:3], v[2:3], 0, s[0:1]
	v_lshl_add_u64 v[4:5], s[6:7], 0, v[0:1]
	s_mov_b64 s[0:1], 0
	s_movk_i32 s3, 0x4000
	s_mov_b64 s[4:5], 0x800
	s_movk_i32 s6, 0x45ff
	v_mov_b32_e32 v1, v176
	v_readlane_b32 s8, v242, 15
	v_readlane_b32 s9, v242, 16
	v_readlane_b32 s12, v242, 19
	v_readlane_b32 s13, v242, 20
	v_readlane_b32 s14, v242, 21
	v_readlane_b32 s15, v242, 22
	v_readlane_b32 s16, v242, 23
	v_readlane_b32 s17, v242, 24
	v_readlane_b32 s18, v242, 25
	v_readlane_b32 s19, v242, 26
	global_load_dword v16, v[4:5], off
	v_lshl_add_u64 v[4:5], v[4:5], 0, s[4:5]
	global_load_dword v17, v[4:5], off
	v_lshl_add_u64 v[4:5], v[4:5], 0, s[4:5]
	global_load_dword v18, v[4:5], off
	v_lshl_add_u64 v[4:5], v[4:5], 0, s[4:5]
	global_load_dword v19, v[4:5], off
	v_lshl_add_u64 v[4:5], v[4:5], 0, s[4:5]
	global_load_dword v20, v[4:5], off
	v_lshl_add_u64 v[4:5], v[4:5], 0, s[4:5]
	global_load_dword v21, v[4:5], off
	v_lshl_add_u64 v[4:5], v[4:5], 0, s[4:5]
	global_load_dword v22, v[4:5], off
	v_lshl_add_u64 v[4:5], v[4:5], 0, s[4:5]
	global_load_dword v23, v[4:5], off
	v_lshl_add_u64 v[4:5], v[4:5], 0, s[4:5]
	global_load_dword v24, v[4:5], off
	v_lshl_add_u64 v[4:5], v[4:5], 0, s[4:5]
	global_load_dword v25, v[4:5], off
	v_lshl_add_u64 v[4:5], v[4:5], 0, s[4:5]
	global_load_dword v26, v[4:5], off
	v_lshl_add_u64 v[4:5], v[4:5], 0, s[4:5]
	global_load_dword v27, v[4:5], off
	v_lshl_add_u64 v[4:5], v[4:5], 0, s[4:5]
	global_load_dword v28, v[4:5], off
	v_lshl_add_u64 v[4:5], v[4:5], 0, s[4:5]
	global_load_dword v29, v[4:5], off
	v_lshl_add_u64 v[4:5], v[4:5], 0, s[4:5]
	global_load_dword v30, v[4:5], off
	v_lshl_add_u64 v[4:5], v[4:5], 0, s[4:5]
	global_load_dword v31, v[4:5], off
	v_lshl_add_u64 v[4:5], v[4:5], 0, s[4:5]
	global_load_dword v32, v[4:5], off
	v_lshl_add_u64 v[4:5], v[4:5], 0, s[4:5]
	global_load_dword v33, v[4:5], off
	v_lshl_add_u64 v[4:5], v[4:5], 0, s[4:5]
	global_load_dword v34, v[4:5], off
	v_lshl_add_u64 v[4:5], v[4:5], 0, s[4:5]
	global_load_dword v35, v[4:5], off
	v_lshl_add_u64 v[4:5], v[4:5], 0, s[4:5]
	global_load_dword v36, v[4:5], off
	v_lshl_add_u64 v[4:5], v[4:5], 0, s[4:5]
	global_load_dword v37, v[4:5], off
	v_lshl_add_u64 v[4:5], v[4:5], 0, s[4:5]
	global_load_dword v38, v[4:5], off
	v_lshl_add_u64 v[4:5], v[4:5], 0, s[4:5]
	global_load_dword v39, v[4:5], off
	v_lshl_add_u64 v[4:5], v[4:5], 0, s[4:5]
	global_load_dword v40, v[4:5], off
	v_lshl_add_u64 v[4:5], v[4:5], 0, s[4:5]
	global_load_dword v41, v[4:5], off
	v_lshl_add_u64 v[4:5], v[4:5], 0, s[4:5]
	global_load_dword v42, v[4:5], off
	v_lshl_add_u64 v[4:5], v[4:5], 0, s[4:5]
	global_load_dword v43, v[4:5], off
	v_lshl_add_u64 v[4:5], v[4:5], 0, s[4:5]
	global_load_dword v44, v[4:5], off
	v_lshl_add_u64 v[4:5], v[4:5], 0, s[4:5]
	global_load_dword v45, v[4:5], off
	v_lshl_add_u64 v[4:5], v[4:5], 0, s[4:5]
	global_load_dword v46, v[4:5], off
	v_lshl_add_u64 v[4:5], v[4:5], 0, s[4:5]
	global_load_dword v47, v[4:5], off
	v_lshl_add_u64 v[4:5], v[4:5], 0, s[4:5]
	s_mov_b64 s[0:1], 0x10000
	v_lshl_add_u64 v[2:3], v[2:3], 0, s[0:1]
	v_add_u32_e32 v56, 0x10000, v6
	s_mov_b64 s[0:1], 0
	global_load_dword v48, v[2:3], off
	v_lshl_add_u64 v[2:3], v[2:3], 0, s[4:5]
	global_load_dword v49, v[2:3], off
	v_lshl_add_u64 v[2:3], v[2:3], 0, s[4:5]
	global_load_dword v50, v[2:3], off
	v_lshl_add_u64 v[2:3], v[2:3], 0, s[4:5]
	global_load_dword v51, v[2:3], off
	v_lshl_add_u64 v[2:3], v[2:3], 0, s[4:5]
	s_waitcnt vmcnt(32)
	v_mul_f32_e32 v52, 0xbfb8aa3b, v16
	v_mul_f32_e32 v53, 0xbfb8aa3b, v17
	v_mul_f32_e32 v54, 0xbfb8aa3b, v18
	v_mul_f32_e32 v55, 0xbfb8aa3b, v19
	v_exp_f32_e32 v52, v52
	v_exp_f32_e32 v53, v53
	v_exp_f32_e32 v54, v54
	v_exp_f32_e32 v55, v55
	v_add_f32_e32 v52, 1.0, v52
	v_add_f32_e32 v53, 1.0, v53
	v_add_f32_e32 v54, 1.0, v54
	v_add_f32_e32 v55, 1.0, v55
	v_rcp_f32_e32 v52, v52
	v_rcp_f32_e32 v53, v53
	v_rcp_f32_e32 v54, v54
	v_rcp_f32_e32 v55, v55
	v_mul_f32_e32 v16, v16, v52
	v_mul_f32_e32 v17, v17, v53
	v_mul_f32_e32 v18, v18, v54
	v_mul_f32_e32 v19, v19, v55
	ds_write_b32 v6, v16
	ds_write_b32 v6, v17 offset:2048
	ds_write_b32 v6, v18 offset:4096
	ds_write_b32 v6, v19 offset:6144
	s_waitcnt vmcnt(28)
	v_mul_f32_e32 v52, 0xbfb8aa3b, v20
	v_mul_f32_e32 v53, 0xbfb8aa3b, v21
	v_mul_f32_e32 v54, 0xbfb8aa3b, v22
	v_mul_f32_e32 v55, 0xbfb8aa3b, v23
	v_exp_f32_e32 v52, v52
	v_exp_f32_e32 v53, v53
	v_exp_f32_e32 v54, v54
	v_exp_f32_e32 v55, v55
	v_add_f32_e32 v52, 1.0, v52
	v_add_f32_e32 v53, 1.0, v53
	v_add_f32_e32 v54, 1.0, v54
	v_add_f32_e32 v55, 1.0, v55
	v_rcp_f32_e32 v52, v52
	v_rcp_f32_e32 v53, v53
	v_rcp_f32_e32 v54, v54
	v_rcp_f32_e32 v55, v55
	v_mul_f32_e32 v20, v20, v52
	v_mul_f32_e32 v21, v21, v53
	v_mul_f32_e32 v22, v22, v54
	v_mul_f32_e32 v23, v23, v55
	ds_write_b32 v6, v20 offset:8192
	ds_write_b32 v6, v21 offset:10240
	ds_write_b32 v6, v22 offset:12288
	ds_write_b32 v6, v23 offset:14336
	s_waitcnt vmcnt(24)
; __device__ __forceinline__ float fast_silu(float x) { return x * fast_sigmoid(x); }
; __device__ __forceinline__ void p0_prologue(const Args& a, LAS unsigned char* lds, int tid, int wid, int lane, int G) {
;     ...
;         for (int i = tid; i < 9 * DM; i += 512) { const float v = i < 8 * DM ? a.c[i] : a.c_ctx[i - 8 * DM]; sl[i] = fast_silu(v); }
;         __syncthreads();
;         const int n = blockIdx.x * 64 + lane;
;         float accv[9];
; #pragma unroll
;         for (int r = 0; r < 9; ++r) accv[r] = 0.f;
;         const float* wp = a.w_mod + (size_t)(wid * 256) * NMOD + n;
	v_mul_f32_e32 v52, 0xbfb8aa3b, v24
	v_mul_f32_e32 v53, 0xbfb8aa3b, v25
	v_mul_f32_e32 v54, 0xbfb8aa3b, v26
	v_mul_f32_e32 v55, 0xbfb8aa3b, v27
	v_exp_f32_e32 v52, v52
	v_exp_f32_e32 v53, v53
	v_exp_f32_e32 v54, v54
	v_exp_f32_e32 v55, v55
	v_add_f32_e32 v52, 1.0, v52
	v_add_f32_e32 v53, 1.0, v53
	v_add_f32_e32 v54, 1.0, v54
	v_add_f32_e32 v55, 1.0, v55
	v_rcp_f32_e32 v52, v52
	v_rcp_f32_e32 v53, v53
	v_rcp_f32_e32 v54, v54
	v_rcp_f32_e32 v55, v55
	v_mul_f32_e32 v24, v24, v52
	v_mul_f32_e32 v25, v25, v53
	v_mul_f32_e32 v26, v26, v54
	v_mul_f32_e32 v27, v27, v55
	ds_write_b32 v6, v24 offset:16384
	ds_write_b32 v6, v25 offset:18432
	ds_write_b32 v6, v26 offset:20480
	ds_write_b32 v6, v27 offset:22528
	s_waitcnt vmcnt(20)
	v_mul_f32_e32 v52, 0xbfb8aa3b, v28
	v_mul_f32_e32 v53, 0xbfb8aa3b, v29
	v_mul_f32_e32 v54, 0xbfb8aa3b, v30
	v_mul_f32_e32 v55, 0xbfb8aa3b, v31
	v_exp_f32_e32 v52, v52
	v_exp_f32_e32 v53, v53
	v_exp_f32_e32 v54, v54
	v_exp_f32_e32 v55, v55
	v_add_f32_e32 v52, 1.0, v52
	v_add_f32_e32 v53, 1.0, v53
	v_add_f32_e32 v54, 1.0, v54
	v_add_f32_e32 v55, 1.0, v55
	v_rcp_f32_e32 v52, v52
	v_rcp_f32_e32 v53, v53
	v_rcp_f32_e32 v54, v54
	v_rcp_f32_e32 v55, v55
	v_mul_f32_e32 v28, v28, v52
	v_mul_f32_e32 v29, v29, v53
	v_mul_f32_e32 v30, v30, v54
	v_mul_f32_e32 v31, v31, v55
	ds_write_b32 v6, v28 offset:24576
	ds_write_b32 v6, v29 offset:26624
	ds_write_b32 v6, v30 offset:28672
	ds_write_b32 v6, v31 offset:30720
	s_waitcnt vmcnt(16)
	v_mul_f32_e32 v52, 0xbfb8aa3b, v32
	v_mul_f32_e32 v53, 0xbfb8aa3b, v33
	v_mul_f32_e32 v54, 0xbfb8aa3b, v34
	v_mul_f32_e32 v55, 0xbfb8aa3b, v35
	v_exp_f32_e32 v52, v52
	v_exp_f32_e32 v53, v53
	v_exp_f32_e32 v54, v54
	v_exp_f32_e32 v55, v55
	v_add_f32_e32 v52, 1.0, v52
	v_add_f32_e32 v53, 1.0, v53
	v_add_f32_e32 v54, 1.0, v54
	v_add_f32_e32 v55, 1.0, v55
	v_rcp_f32_e32 v52, v52
	v_rcp_f32_e32 v53, v53
	v_rcp_f32_e32 v54, v54
	v_rcp_f32_e32 v55, v55
	v_mul_f32_e32 v32, v32, v52
	v_mul_f32_e32 v33, v33, v53
	v_mul_f32_e32 v34, v34, v54
	v_mul_f32_e32 v35, v35, v55
	ds_write_b32 v6, v32 offset:32768
	ds_write_b32 v6, v33 offset:34816
	ds_write_b32 v6, v34 offset:36864
	ds_write_b32 v6, v35 offset:38912
	s_waitcnt vmcnt(12)
	v_mul_f32_e32 v52, 0xbfb8aa3b, v36
	v_mul_f32_e32 v53, 0xbfb8aa3b, v37
	v_mul_f32_e32 v54, 0xbfb8aa3b, v38
	v_mul_f32_e32 v55, 0xbfb8aa3b, v39
	v_exp_f32_e32 v52, v52
	v_exp_f32_e32 v53, v53
	v_exp_f32_e32 v54, v54
	v_exp_f32_e32 v55, v55
	v_add_f32_e32 v52, 1.0, v52
	v_add_f32_e32 v53, 1.0, v53
	v_add_f32_e32 v54, 1.0, v54
	v_add_f32_e32 v55, 1.0, v55
	v_rcp_f32_e32 v52, v52
	v_rcp_f32_e32 v53, v53
	v_rcp_f32_e32 v54, v54
	v_rcp_f32_e32 v55, v55
	v_mul_f32_e32 v36, v36, v52
	v_mul_f32_e32 v37, v37, v53
	v_mul_f32_e32 v38, v38, v54
	v_mul_f32_e32 v39, v39, v55
	ds_write_b32 v6, v36 offset:40960
	ds_write_b32 v6, v37 offset:43008
	ds_write_b32 v6, v38 offset:45056
	ds_write_b32 v6, v39 offset:47104
	s_waitcnt vmcnt(8)
	v_mul_f32_e32 v52, 0xbfb8aa3b, v40
	v_mul_f32_e32 v53, 0xbfb8aa3b, v41
	v_mul_f32_e32 v54, 0xbfb8aa3b, v42
	v_mul_f32_e32 v55, 0xbfb8aa3b, v43
	v_exp_f32_e32 v52, v52
	v_exp_f32_e32 v53, v53
	v_exp_f32_e32 v54, v54
	v_exp_f32_e32 v55, v55
	v_add_f32_e32 v52, 1.0, v52
	v_add_f32_e32 v53, 1.0, v53
	v_add_f32_e32 v54, 1.0, v54
	v_add_f32_e32 v55, 1.0, v55
	v_rcp_f32_e32 v52, v52
	v_rcp_f32_e32 v53, v53
	v_rcp_f32_e32 v54, v54
	v_rcp_f32_e32 v55, v55
	v_mul_f32_e32 v40, v40, v52
	v_mul_f32_e32 v41, v41, v53
	v_mul_f32_e32 v42, v42, v54
	v_mul_f32_e32 v43, v43, v55
	ds_write_b32 v6, v40 offset:49152
	ds_write_b32 v6, v41 offset:51200
	ds_write_b32 v6, v42 offset:53248
	ds_write_b32 v6, v43 offset:55296
	s_waitcnt vmcnt(4)
	v_mul_f32_e32 v52, 0xbfb8aa3b, v44
	v_mul_f32_e32 v53, 0xbfb8aa3b, v45
	v_mul_f32_e32 v54, 0xbfb8aa3b, v46
	v_mul_f32_e32 v55, 0xbfb8aa3b, v47
	v_exp_f32_e32 v52, v52
	v_exp_f32_e32 v53, v53
	v_exp_f32_e32 v54, v54
	v_exp_f32_e32 v55, v55
	v_add_f32_e32 v52, 1.0, v52
	v_add_f32_e32 v53, 1.0, v53
	v_add_f32_e32 v54, 1.0, v54
	v_add_f32_e32 v55, 1.0, v55
	v_rcp_f32_e32 v52, v52
	v_rcp_f32_e32 v53, v53
	v_rcp_f32_e32 v54, v54
	v_rcp_f32_e32 v55, v55
	v_mul_f32_e32 v44, v44, v52
	v_mul_f32_e32 v45, v45, v53
	v_mul_f32_e32 v46, v46, v54
	v_mul_f32_e32 v47, v47, v55
	ds_write_b32 v6, v44 offset:57344
	ds_write_b32 v6, v45 offset:59392
	ds_write_b32 v6, v46 offset:61440
	ds_write_b32 v6, v47 offset:63488
	s_waitcnt vmcnt(0)
	v_mul_f32_e32 v52, 0xbfb8aa3b, v48
	v_mul_f32_e32 v53, 0xbfb8aa3b, v49
	v_mul_f32_e32 v54, 0xbfb8aa3b, v50
	v_mul_f32_e32 v55, 0xbfb8aa3b, v51
	v_exp_f32_e32 v52, v52
	v_exp_f32_e32 v53, v53
	v_exp_f32_e32 v54, v54
	v_exp_f32_e32 v55, v55
	v_add_f32_e32 v52, 1.0, v52
	v_add_f32_e32 v53, 1.0, v53
	v_add_f32_e32 v54, 1.0, v54
	v_add_f32_e32 v55, 1.0, v55
	v_rcp_f32_e32 v52, v52
	v_rcp_f32_e32 v53, v53
	v_rcp_f32_e32 v54, v54
	v_rcp_f32_e32 v55, v55
	v_mul_f32_e32 v48, v48, v52
	v_mul_f32_e32 v49, v49, v53
	v_mul_f32_e32 v50, v50, v54
	v_mul_f32_e32 v51, v51, v55
	ds_write_b32 v56, v48
	ds_write_b32 v56, v49 offset:2048
	ds_write_b32 v56, v50 offset:4096
	ds_write_b32 v56, v51 offset:6144
	s_or_b64 exec, exec, s[0:1]
	s_lshl_b32 s0, s92, 8
	s_mul_hi_u32 s7, s0, 0xc000
	s_lshl_b32 s0, s92, 10
	v_readlane_b32 s8, v242, 11
	s_lshl_b32 s4, s2, 6
	s_mul_i32 s1, s92, 0xc00000
	s_add_i32 s6, s0, 0
	v_readlane_b32 s16, v242, 19
	v_or_b32_e32 v2, s4, v177
	v_readlane_b32 s17, v242, 20
	s_add_u32 s0, s16, s1
	v_ashrrev_i32_e32 v3, 31, v2
	s_addc_u32 s1, s17, s7
	v_readlane_b32 s9, v242, 12
	v_readlane_b32 s10, v242, 13
	v_readlane_b32 s11, v242, 14
	v_readlane_b32 s12, v242, 15
	v_readlane_b32 s13, v242, 16
	v_readlane_b32 s14, v242, 17
	v_readlane_b32 s15, v242, 18
	v_readlane_b32 s18, v242, 21
	v_readlane_b32 s19, v242, 22
	v_readlane_b32 s20, v242, 23
	v_readlane_b32 s21, v242, 24
	v_lshl_add_u64 v[4:5], v[2:3], 2, s[0:1]
	s_mov_b64 s[0:1], 0x60000
	v_mov_b32_e32 v6, 0
	s_mov_b32 s3, 0xc000
	s_mov_b32 s5, 0
	v_lshl_add_u64 v[4:5], v[4:5], 0, s[0:1]
	s_mov_b32 s7, 0xfffac000
	s_mov_b32 s8, 0xfffb8000
	s_mov_b32 s9, 0xfffc4000
	s_mov_b32 s12, 0xfffd0000
	s_mov_b32 s13, 0xfffdc000
	s_mov_b32 s14, 0xfffe8000
	s_mov_b32 s15, 0xffff4000
	s_mov_b32 s16, 0x18000
	s_mov_b32 s17, 0x24000
	s_mov_b32 s18, 0x30000
	s_mov_b32 s19, 0x3c000
	s_mov_b32 s20, 0x48000
	s_mov_b32 s21, 0x54000
	s_mov_b64 s[10:11], 0xc0000
	v_mov_b32_e32 v7, v6
	v_mov_b32_e32 v8, v6
	v_mov_b32_e32 v9, v6
	v_mov_b32_e32 v10, v6
	v_mov_b32_e32 v11, v6
	v_mov_b32_e32 v12, v6
	v_mov_b32_e32 v13, v6
	v_mov_b32_e32 v1, v6
	s_waitcnt lgkmcnt(0)
	s_barrier
	v_readlane_b32 s22, v242, 25
	v_readlane_b32 s23, v242, 26

; __device__ __forceinline__ void p0_prologue(const Args& a, LAS unsigned char* lds, int tid, int wid, int lane, int G) {
;     ...
;     constexpr int I_IN = 32 * 256, I_SQ = 32 * 32, NITEMS = I_IN + 3 * I_SQ;
;     const int nfree = G > 192 ? G - 192 : 0, E = nfree * 8 * 4 < NITEMS ? nfree * 8 * 4 : NITEMS;
;     const bool isfree = (int)blockIdx.x >= 192;
;     for (int it = isfree ? ((int)blockIdx.x - 192) * 8 + wid : E + gw; it < NITEMS; ) {
;         int r = it;
;         it = (it < E) ? ((it + nfree * 8 < E) ? it + nfree * 8 : E + gw) : it + NGW;
.LBB0_46:
	s_lshl_b32 s0, s2, 3
	s_add_i32 s93, s92, s0
	s_max_i32 s0, s30, 0xc0
	s_lshl_b32 s3, s0, 3
	s_addk_i32 s3, 0xfa00
	s_min_i32 s0, s3, 0xb00
	s_mul_i32 s6, s0, 8
	s_lshl_b32 s96, s30, 3
	s_add_i32 s0, s93, 0xfffffa00
	s_add_i32 s7, s6, s93
	s_cmpk_gt_i32 s2, 0xbf
	s_cselect_b32 s8, s0, s7
	s_cmpk_gt_i32 s8, 0x2bff
	s_cbranch_scc1 .LBB0_69
	v_lshlrev_b32_e32 v0, 3, v176
	v_and_b32_e32 v0, 56, v0
	v_mul_u32_u24_e32 v2, 0x104, v0
	v_lshlrev_b32_e32 v0, 1, v0
	v_mov_b32_e32 v1, 0
	s_mul_i32 s0, s92, 0x4100
	v_lshrrev_b32_e32 v11, 3, v177
	v_lshl_add_u64 v[6:7], s[28:29], 0, v[0:1]
	s_mov_b64 s[4:5], 0x5300000
	s_add_i32 s0, s0, 0
	v_lshl_add_u64 v[0:1], v[6:7], 0, s[4:5]
	v_lshlrev_b32_e32 v3, 2, v11
	s_mov_b64 s[4:5], 0x4b00000
	v_add3_u32 v12, s0, v2, v3
	v_lshl_add_u64 v[2:3], v[6:7], 0, s[4:5]
	s_mov_b64 s[4:5], 0x4300000
	v_lshl_add_u64 v[4:5], v[6:7], 0, s[4:5]
	v_lshlrev_b32_e32 v8, 6, v176
	s_mov_b64 s[4:5], 0x9b00000
	s_mov_b32 s1, 0
	v_lshl_add_u32 v10, v177, 2, s0
	v_or_b32_e32 v13, 8, v11
	v_or_b32_e32 v14, 16, v11
	v_or_b32_e32 v15, 24, v11
	v_or_b32_e32 v16, 32, v11
	v_or_b32_e32 v17, 40, v11
	v_or_b32_e32 v18, 48, v11
	v_or_b32_e32 v19, 56, v11
	v_and_b32_e32 v20, 64, v8
	v_lshl_add_u64 v[6:7], v[6:7], 0, s[4:5]
	s_movk_i32 s9, 0xfff
	v_add_u32_e32 v21, 0x400, v12
	s_branch .LBB0_49
